# attention vector segment: four row-sum accumulators instead of two
# speedup vs baseline: 1.0004x; 1.0004x over previous
.Lattn_tb4:
	ds_read_b128 v[216:219], v187 offset:16384
	ds_read_b128 v[220:223], v187 offset:20480
	ds_read_b128 v[224:227], v187 offset:24576
	ds_read_b128 v[228:231], v187 offset:28672
	ds_read_b128 v[208:211], v188 offset:16384
	ds_read_b128 v[212:215], v188 offset:20480
	v_exp_f32_e32 v171, v96
	v_exp_f32_e32 v173, v97
	v_exp_f32_e32 v179, v98
	s_add_i32 m0, s5, 16384
	v_exp_f32_e32 v180, v99
	v_exp_f32_e32 v232, v100
	v_exp_f32_e32 v233, v101
	global_load_lds_dwordx4 v170, s[48:49]
	v_exp_f32_e32 v234, v102
	v_exp_f32_e32 v235, v103
	v_add_f32_e32 v190, v171, v232
	s_add_i32 m0, s5, 24576
	v_add_f32_e32 v191, v173, v233
	v_add_f32_e32 v254, v179, v234
	v_add_f32_e32 v255, v180, v235
	global_load_lds_dwordx4 v170, s[50:51]
	v_cvt_pk_bf16_f32 v144, v171, v173
	v_cvt_pk_bf16_f32 v145, v179, v180
	v_cvt_pk_bf16_f32 v146, v232, v233
	s_add_i32 m0, s5, 114688
	v_cvt_pk_bf16_f32 v147, v234, v235
	v_exp_f32_e32 v171, v104
	v_exp_f32_e32 v173, v105
	global_load_lds_dwordx4 v172, s[52:53]
	v_exp_f32_e32 v179, v106
	v_exp_f32_e32 v180, v107
	v_exp_f32_e32 v232, v108
	s_add_i32 m0, s5, 122880
	v_exp_f32_e32 v233, v109
	v_exp_f32_e32 v234, v110
	v_exp_f32_e32 v235, v111
	global_load_lds_dwordx4 v172, s[54:55]
	v_add_f32_e32 v190, v190, v171
	v_add_f32_e32 v191, v191, v173
	v_add_f32_e32 v254, v254, v179
	v_add_f32_e32 v255, v255, v180
	v_add_f32_e32 v190, v190, v232
	v_add_f32_e32 v191, v191, v233
	v_add_f32_e32 v254, v254, v234
	v_add_f32_e32 v255, v255, v235
	v_cvt_pk_bf16_f32 v148, v171, v173
	v_cvt_pk_bf16_f32 v149, v179, v180
	v_cvt_pk_bf16_f32 v150, v232, v233
	v_cvt_pk_bf16_f32 v151, v234, v235
	v_exp_f32_e32 v171, v112
	v_exp_f32_e32 v173, v113
	v_exp_f32_e32 v179, v114
	v_exp_f32_e32 v180, v115
	v_exp_f32_e32 v232, v116
	v_exp_f32_e32 v233, v117
	v_exp_f32_e32 v234, v118
	v_exp_f32_e32 v235, v119
	v_add_f32_e32 v190, v190, v171
	v_add_f32_e32 v191, v191, v173
	v_add_f32_e32 v254, v254, v179
	v_add_f32_e32 v255, v255, v180
	v_add_f32_e32 v190, v190, v232
	v_add_f32_e32 v191, v191, v233
	v_add_f32_e32 v254, v254, v234
	v_add_f32_e32 v255, v255, v235
	v_cvt_pk_bf16_f32 v152, v171, v173
	v_cvt_pk_bf16_f32 v153, v179, v180
	v_cvt_pk_bf16_f32 v154, v232, v233
	v_cvt_pk_bf16_f32 v155, v234, v235
	v_exp_f32_e32 v171, v120
	v_exp_f32_e32 v173, v121
	v_exp_f32_e32 v179, v122
	v_exp_f32_e32 v180, v123
	v_exp_f32_e32 v232, v124
	v_exp_f32_e32 v233, v125
	v_exp_f32_e32 v234, v126
	v_exp_f32_e32 v235, v127
	v_add_f32_e32 v190, v190, v171
	v_add_f32_e32 v191, v191, v173
	v_add_f32_e32 v254, v254, v179
	v_add_f32_e32 v255, v255, v180
	v_add_f32_e32 v190, v190, v232
	v_add_f32_e32 v191, v191, v233
	v_add_f32_e32 v254, v254, v234
	v_add_f32_e32 v255, v255, v235
	v_add_f32_e32 v190, v190, v254
	v_add_f32_e32 v191, v191, v255
	v_add_f32_e32 v190, v190, v191
	v_cmp_ngt_f32_e32 vcc, 0x71800000, v190
	v_cvt_pk_bf16_f32 v156, v171, v173
	v_cvt_pk_bf16_f32 v157, v179, v180
	v_cvt_pk_bf16_f32 v158, v232, v233
	v_cvt_pk_bf16_f32 v159, v234, v235
	s_nop 0
	s_cbranch_vccnz .Lattn_redo_L0
	v_add_f32_e32 v167, v167, v190
	s_cmp_lg_u32 s14, 0
	s_cbranch_scc1 .Lattn_tb5
	s_waitcnt vmcnt(4)
	s_barrier

.Lattn_tb6:
	ds_read_b128 v[216:219], v187 offset:32768
	ds_read_b128 v[220:223], v187 offset:36864
	ds_read_b128 v[224:227], v187 offset:40960
	ds_read_b128 v[228:231], v187 offset:45056
	ds_read_b128 v[208:211], v188 offset:32768
	ds_read_b128 v[212:215], v188 offset:36864
	v_exp_f32_e32 v171, v64
	v_exp_f32_e32 v173, v65
	v_exp_f32_e32 v179, v66
	s_add_i32 m0, s5, 32768
	v_exp_f32_e32 v180, v67
	v_exp_f32_e32 v232, v68
	v_exp_f32_e32 v233, v69
	global_load_lds_dwordx4 v170, s[48:49]
	v_exp_f32_e32 v234, v70
	v_exp_f32_e32 v235, v71
	v_add_f32_e32 v190, v171, v232
	s_add_i32 m0, s5, 40960
	v_add_f32_e32 v191, v173, v233
	v_add_f32_e32 v254, v179, v234
	v_add_f32_e32 v255, v180, v235
	global_load_lds_dwordx4 v170, s[50:51]
	v_cvt_pk_bf16_f32 v144, v171, v173
	v_cvt_pk_bf16_f32 v145, v179, v180
	v_cvt_pk_bf16_f32 v146, v232, v233
	s_add_i32 m0, s5, 65536
	v_cvt_pk_bf16_f32 v147, v234, v235
	v_exp_f32_e32 v171, v72
	v_exp_f32_e32 v173, v73
	global_load_lds_dwordx4 v172, s[52:53]
	v_exp_f32_e32 v179, v74
	v_exp_f32_e32 v180, v75
	v_exp_f32_e32 v232, v76
	s_add_i32 m0, s5, 73728
	v_exp_f32_e32 v233, v77
	v_exp_f32_e32 v234, v78
	v_exp_f32_e32 v235, v79
	global_load_lds_dwordx4 v172, s[54:55]
	v_add_f32_e32 v190, v190, v171
	v_add_f32_e32 v191, v191, v173
	v_add_f32_e32 v254, v254, v179
	v_add_f32_e32 v255, v255, v180
	v_add_f32_e32 v190, v190, v232
	v_add_f32_e32 v191, v191, v233
	v_add_f32_e32 v254, v254, v234
	v_add_f32_e32 v255, v255, v235
	v_cvt_pk_bf16_f32 v148, v171, v173
	v_cvt_pk_bf16_f32 v149, v179, v180
	v_cvt_pk_bf16_f32 v150, v232, v233
	v_cvt_pk_bf16_f32 v151, v234, v235
	v_exp_f32_e32 v171, v80
	v_exp_f32_e32 v173, v81
	v_exp_f32_e32 v179, v82
	v_exp_f32_e32 v180, v83
	v_exp_f32_e32 v232, v84
	v_exp_f32_e32 v233, v85
	v_exp_f32_e32 v234, v86
	v_exp_f32_e32 v235, v87
	v_add_f32_e32 v190, v190, v171
	v_add_f32_e32 v191, v191, v173
	v_add_f32_e32 v254, v254, v179
	v_add_f32_e32 v255, v255, v180
	v_add_f32_e32 v190, v190, v232
	v_add_f32_e32 v191, v191, v233
	v_add_f32_e32 v254, v254, v234
	v_add_f32_e32 v255, v255, v235
	v_cvt_pk_bf16_f32 v152, v171, v173
	v_cvt_pk_bf16_f32 v153, v179, v180
	v_cvt_pk_bf16_f32 v154, v232, v233
	v_cvt_pk_bf16_f32 v155, v234, v235
	v_exp_f32_e32 v171, v88
	v_exp_f32_e32 v173, v89
	v_exp_f32_e32 v179, v90
	v_exp_f32_e32 v180, v91
	v_exp_f32_e32 v232, v92
	v_exp_f32_e32 v233, v93
	v_exp_f32_e32 v234, v94
	v_exp_f32_e32 v235, v95
	v_add_f32_e32 v190, v190, v171
	v_add_f32_e32 v191, v191, v173
	v_add_f32_e32 v254, v254, v179
	v_add_f32_e32 v255, v255, v180
	v_add_f32_e32 v190, v190, v232
	v_add_f32_e32 v191, v191, v233
	v_add_f32_e32 v254, v254, v234
	v_add_f32_e32 v255, v255, v235
	v_add_f32_e32 v190, v190, v254
	v_add_f32_e32 v191, v191, v255
	v_add_f32_e32 v190, v190, v191
	v_cmp_ngt_f32_e32 vcc, 0x71800000, v190
	v_cvt_pk_bf16_f32 v156, v171, v173
	v_cvt_pk_bf16_f32 v157, v179, v180
	v_cvt_pk_bf16_f32 v158, v232, v233
	v_cvt_pk_bf16_f32 v159, v234, v235
	s_nop 0
	s_cbranch_vccnz .Lattn_redo_L1
	v_add_f32_e32 v167, v167, v190
	s_cmp_lg_u32 s14, 0
	s_cbranch_scc1 .Lattn_tb7
	s_waitcnt vmcnt(4)
	s_barrier

.Lattn_tb8:
	ds_read_b128 v[216:219], v187 offset:49152
	ds_read_b128 v[220:223], v187 offset:53248
	ds_read_b128 v[224:227], v187 offset:57344
	ds_read_b128 v[228:231], v187 offset:61440
	ds_read_b128 v[208:211], v188 offset:49152
	ds_read_b128 v[212:215], v188 offset:53248
	v_exp_f32_e32 v171, v96
	v_exp_f32_e32 v173, v97
	v_exp_f32_e32 v179, v98
	s_add_i32 m0, s5, 49152
	v_exp_f32_e32 v180, v99
	v_exp_f32_e32 v232, v100
	v_exp_f32_e32 v233, v101
	global_load_lds_dwordx4 v170, s[48:49]
	v_exp_f32_e32 v234, v102
	v_exp_f32_e32 v235, v103
	v_add_f32_e32 v190, v171, v232
	s_add_i32 m0, s5, 57344
	v_add_f32_e32 v191, v173, v233
	v_add_f32_e32 v254, v179, v234
	v_add_f32_e32 v255, v180, v235
	global_load_lds_dwordx4 v170, s[50:51]
	v_cvt_pk_bf16_f32 v144, v171, v173
	v_cvt_pk_bf16_f32 v145, v179, v180
	v_cvt_pk_bf16_f32 v146, v232, v233
	s_add_i32 m0, s5, 81920
	v_cvt_pk_bf16_f32 v147, v234, v235
	v_exp_f32_e32 v171, v104
	v_exp_f32_e32 v173, v105
	global_load_lds_dwordx4 v172, s[52:53]
	v_exp_f32_e32 v179, v106
	v_exp_f32_e32 v180, v107
	v_exp_f32_e32 v232, v108
	s_add_i32 m0, s5, 90112
	v_exp_f32_e32 v233, v109
	v_exp_f32_e32 v234, v110
	v_exp_f32_e32 v235, v111
	global_load_lds_dwordx4 v172, s[54:55]
	v_add_f32_e32 v190, v190, v171
	v_add_f32_e32 v191, v191, v173
	v_add_f32_e32 v254, v254, v179
	v_add_f32_e32 v255, v255, v180
	v_add_f32_e32 v190, v190, v232
	v_add_f32_e32 v191, v191, v233
	v_add_f32_e32 v254, v254, v234
	v_add_f32_e32 v255, v255, v235
	v_cvt_pk_bf16_f32 v148, v171, v173
	v_cvt_pk_bf16_f32 v149, v179, v180
	v_cvt_pk_bf16_f32 v150, v232, v233
	v_cvt_pk_bf16_f32 v151, v234, v235
	v_exp_f32_e32 v171, v112
	v_exp_f32_e32 v173, v113
	v_exp_f32_e32 v179, v114
	v_exp_f32_e32 v180, v115
	v_exp_f32_e32 v232, v116
	v_exp_f32_e32 v233, v117
	v_exp_f32_e32 v234, v118
	v_exp_f32_e32 v235, v119
	v_add_f32_e32 v190, v190, v171
	v_add_f32_e32 v191, v191, v173
	v_add_f32_e32 v254, v254, v179
	v_add_f32_e32 v255, v255, v180
	v_add_f32_e32 v190, v190, v232
	v_add_f32_e32 v191, v191, v233
	v_add_f32_e32 v254, v254, v234
	v_add_f32_e32 v255, v255, v235
	v_cvt_pk_bf16_f32 v152, v171, v173
	v_cvt_pk_bf16_f32 v153, v179, v180
	v_cvt_pk_bf16_f32 v154, v232, v233
	v_cvt_pk_bf16_f32 v155, v234, v235
	v_exp_f32_e32 v171, v120
	v_exp_f32_e32 v173, v121
	v_exp_f32_e32 v179, v122
	v_exp_f32_e32 v180, v123
	v_exp_f32_e32 v232, v124
	v_exp_f32_e32 v233, v125
	v_exp_f32_e32 v234, v126
	v_exp_f32_e32 v235, v127
	v_add_f32_e32 v190, v190, v171
	v_add_f32_e32 v191, v191, v173
	v_add_f32_e32 v254, v254, v179
	v_add_f32_e32 v255, v255, v180
	v_add_f32_e32 v190, v190, v232
	v_add_f32_e32 v191, v191, v233
	v_add_f32_e32 v254, v254, v234
	v_add_f32_e32 v255, v255, v235
	v_add_f32_e32 v190, v190, v254
	v_add_f32_e32 v191, v191, v255
	v_add_f32_e32 v190, v190, v191
	v_cmp_ngt_f32_e32 vcc, 0x71800000, v190
	v_cvt_pk_bf16_f32 v156, v171, v173
	v_cvt_pk_bf16_f32 v157, v179, v180
	v_cvt_pk_bf16_f32 v158, v232, v233
	v_cvt_pk_bf16_f32 v159, v234, v235
	s_nop 0
	s_cbranch_vccnz .Lattn_redo_L2
	v_add_f32_e32 v167, v167, v190
	s_cmp_lg_u32 s14, 0
	s_cbranch_scc1 .Lattn_tb9
	s_waitcnt vmcnt(4)
	s_barrier

.Lattn_tb10:
	ds_read_b128 v[216:219], v187 offset:0
	ds_read_b128 v[220:223], v187 offset:4096
	ds_read_b128 v[224:227], v187 offset:8192
	ds_read_b128 v[228:231], v187 offset:12288
	ds_read_b128 v[208:211], v188 offset:0
	ds_read_b128 v[212:215], v188 offset:4096
	v_exp_f32_e32 v171, v64
	v_exp_f32_e32 v173, v65
	v_exp_f32_e32 v179, v66
	s_add_i32 m0, s5, 0
	v_exp_f32_e32 v180, v67
	v_exp_f32_e32 v232, v68
	v_exp_f32_e32 v233, v69
	global_load_lds_dwordx4 v170, s[48:49]
	v_exp_f32_e32 v234, v70
	v_exp_f32_e32 v235, v71
	v_add_f32_e32 v190, v171, v232
	s_add_i32 m0, s5, 8192
	v_add_f32_e32 v191, v173, v233
	v_add_f32_e32 v254, v179, v234
	v_add_f32_e32 v255, v180, v235
	global_load_lds_dwordx4 v170, s[50:51]
	v_cvt_pk_bf16_f32 v144, v171, v173
	v_cvt_pk_bf16_f32 v145, v179, v180
	v_cvt_pk_bf16_f32 v146, v232, v233
	s_add_i32 m0, s5, 98304
	v_cvt_pk_bf16_f32 v147, v234, v235
	v_exp_f32_e32 v171, v72
	v_exp_f32_e32 v173, v73
	global_load_lds_dwordx4 v172, s[52:53]
	v_exp_f32_e32 v179, v74
	v_exp_f32_e32 v180, v75
	v_exp_f32_e32 v232, v76
	s_add_i32 m0, s5, 106496
	v_exp_f32_e32 v233, v77
	v_exp_f32_e32 v234, v78
	v_exp_f32_e32 v235, v79
	global_load_lds_dwordx4 v172, s[54:55]
	v_add_f32_e32 v190, v190, v171
	v_add_f32_e32 v191, v191, v173
	v_add_f32_e32 v254, v254, v179
	v_add_f32_e32 v255, v255, v180
	v_add_f32_e32 v190, v190, v232
	v_add_f32_e32 v191, v191, v233
	v_add_f32_e32 v254, v254, v234
	v_add_f32_e32 v255, v255, v235
	v_cvt_pk_bf16_f32 v148, v171, v173
	v_cvt_pk_bf16_f32 v149, v179, v180
	v_cvt_pk_bf16_f32 v150, v232, v233
	v_cvt_pk_bf16_f32 v151, v234, v235
	v_exp_f32_e32 v171, v80
	v_exp_f32_e32 v173, v81
	v_exp_f32_e32 v179, v82
	v_exp_f32_e32 v180, v83
	v_exp_f32_e32 v232, v84
	v_exp_f32_e32 v233, v85
	v_exp_f32_e32 v234, v86
	v_exp_f32_e32 v235, v87
	v_add_f32_e32 v190, v190, v171
	v_add_f32_e32 v191, v191, v173
	v_add_f32_e32 v254, v254, v179
	v_add_f32_e32 v255, v255, v180
	v_add_f32_e32 v190, v190, v232
	v_add_f32_e32 v191, v191, v233
	v_add_f32_e32 v254, v254, v234
	v_add_f32_e32 v255, v255, v235
	v_cvt_pk_bf16_f32 v152, v171, v173
	v_cvt_pk_bf16_f32 v153, v179, v180
	v_cvt_pk_bf16_f32 v154, v232, v233
	v_cvt_pk_bf16_f32 v155, v234, v235
	v_exp_f32_e32 v171, v88
	v_exp_f32_e32 v173, v89
	v_exp_f32_e32 v179, v90
	v_exp_f32_e32 v180, v91
	v_exp_f32_e32 v232, v92
	v_exp_f32_e32 v233, v93
	v_exp_f32_e32 v234, v94
	v_exp_f32_e32 v235, v95
	v_add_f32_e32 v190, v190, v171
	v_add_f32_e32 v191, v191, v173
	v_add_f32_e32 v254, v254, v179
	v_add_f32_e32 v255, v255, v180
	v_add_f32_e32 v190, v190, v232
	v_add_f32_e32 v191, v191, v233
	v_add_f32_e32 v254, v254, v234
	v_add_f32_e32 v255, v255, v235
	v_add_f32_e32 v190, v190, v254
	v_add_f32_e32 v191, v191, v255
	v_add_f32_e32 v190, v190, v191
	v_cmp_ngt_f32_e32 vcc, 0x71800000, v190
	v_cvt_pk_bf16_f32 v156, v171, v173
	v_cvt_pk_bf16_f32 v157, v179, v180
	v_cvt_pk_bf16_f32 v158, v232, v233
	v_cvt_pk_bf16_f32 v159, v234, v235
	s_nop 0
	s_cbranch_vccnz .Lattn_redo_L3
	v_add_f32_e32 v167, v167, v190
	s_add_i32 s42, s42, 4
	s_add_i32 s47, s47, -1
	s_cmp_lg_u32 s47, 0
	s_cbranch_scc1 .Lattn_loop_f
	s_cmp_lg_u32 s14, 0
	s_cbranch_scc1 .Lattn_tb11
	s_waitcnt vmcnt(4)
	s_barrier

.Lattn_tb12:
	ds_read_b128 v[216:219], v187 offset:16384
	ds_read_b128 v[220:223], v187 offset:20480
	ds_read_b128 v[224:227], v187 offset:24576
	ds_read_b128 v[228:231], v187 offset:28672
	ds_read_b128 v[208:211], v188 offset:16384
	ds_read_b128 v[212:215], v188 offset:20480
	v_exp_f32_e32 v171, v96
	v_exp_f32_e32 v173, v97
	v_exp_f32_e32 v179, v98
	s_add_i32 m0, s5, 114688
	v_exp_f32_e32 v180, v99
	v_exp_f32_e32 v232, v100
	v_exp_f32_e32 v233, v101
	global_load_lds_dwordx4 v172, s[52:53]
	v_exp_f32_e32 v234, v102
	v_exp_f32_e32 v235, v103
	v_add_f32_e32 v190, v171, v232
	s_add_i32 m0, s5, 122880
	v_add_f32_e32 v191, v173, v233
	v_add_f32_e32 v254, v179, v234
	v_add_f32_e32 v255, v180, v235
	global_load_lds_dwordx4 v172, s[54:55]
	v_cvt_pk_bf16_f32 v144, v171, v173
	v_cvt_pk_bf16_f32 v145, v179, v180
	v_cvt_pk_bf16_f32 v146, v232, v233
	v_cvt_pk_bf16_f32 v147, v234, v235
	v_exp_f32_e32 v171, v104
	v_exp_f32_e32 v173, v105
	v_exp_f32_e32 v179, v106
	v_exp_f32_e32 v180, v107
	v_exp_f32_e32 v232, v108
	v_exp_f32_e32 v233, v109
	v_exp_f32_e32 v234, v110
	v_exp_f32_e32 v235, v111
	v_add_f32_e32 v190, v190, v171
	v_add_f32_e32 v191, v191, v173
	v_add_f32_e32 v254, v254, v179
	v_add_f32_e32 v255, v255, v180
	v_add_f32_e32 v190, v190, v232
	v_add_f32_e32 v191, v191, v233
	v_add_f32_e32 v254, v254, v234
	v_add_f32_e32 v255, v255, v235
	v_cvt_pk_bf16_f32 v148, v171, v173
	v_cvt_pk_bf16_f32 v149, v179, v180
	v_cvt_pk_bf16_f32 v150, v232, v233
	v_cvt_pk_bf16_f32 v151, v234, v235
	v_exp_f32_e32 v171, v112
	v_exp_f32_e32 v173, v113
	v_exp_f32_e32 v179, v114
	v_exp_f32_e32 v180, v115
	v_exp_f32_e32 v232, v116
	v_exp_f32_e32 v233, v117
	v_exp_f32_e32 v234, v118
	v_exp_f32_e32 v235, v119
	v_add_f32_e32 v190, v190, v171
	v_add_f32_e32 v191, v191, v173
	v_add_f32_e32 v254, v254, v179
	v_add_f32_e32 v255, v255, v180
	v_add_f32_e32 v190, v190, v232
	v_add_f32_e32 v191, v191, v233
	v_add_f32_e32 v254, v254, v234
	v_add_f32_e32 v255, v255, v235
	v_cvt_pk_bf16_f32 v152, v171, v173
	v_cvt_pk_bf16_f32 v153, v179, v180
	v_cvt_pk_bf16_f32 v154, v232, v233
	v_cvt_pk_bf16_f32 v155, v234, v235
	v_exp_f32_e32 v171, v120
	v_exp_f32_e32 v173, v121
	v_exp_f32_e32 v179, v122
	v_exp_f32_e32 v180, v123
	v_exp_f32_e32 v232, v124
	v_exp_f32_e32 v233, v125
	v_exp_f32_e32 v234, v126
	v_exp_f32_e32 v235, v127
	v_add_f32_e32 v190, v190, v171
	v_add_f32_e32 v191, v191, v173
	v_add_f32_e32 v254, v254, v179
	v_add_f32_e32 v255, v255, v180
	v_add_f32_e32 v190, v190, v232
	v_add_f32_e32 v191, v191, v233
	v_add_f32_e32 v254, v254, v234
	v_add_f32_e32 v255, v255, v235
	v_add_f32_e32 v190, v190, v254
	v_add_f32_e32 v191, v191, v255
	v_add_f32_e32 v190, v190, v191
	v_cmp_ngt_f32_e32 vcc, 0x71800000, v190
	v_cvt_pk_bf16_f32 v156, v171, v173
	v_cvt_pk_bf16_f32 v157, v179, v180
	v_cvt_pk_bf16_f32 v158, v232, v233
	v_cvt_pk_bf16_f32 v159, v234, v235
	s_nop 0
	s_cbranch_vccnz .Lattn_redo_T29
	v_add_f32_e32 v167, v167, v190
	s_cmp_lg_u32 s14, 0
	s_cbranch_scc1 .Lattn_tb13
	s_waitcnt vmcnt(2)
	s_barrier

.Lattn_pfka_f:
	v_exp_f32_e32 v234, v70
	v_exp_f32_e32 v235, v71
	v_add_f32_e32 v190, v171, v232
	s_cmp_lg_u32 s35, 0
	s_cbranch_scc0 .Lattn_pfkb_f
	s_add_i32 s2, s31, 1
	s_and_b32 s2, s2, 31
	s_mul_i32 s2, s2, 0x44000
	s_add_i32 m0, s5, 16384
	s_add_u32 s40, s26, s2
	s_addc_u32 s41, s27, 0
	s_add_u32 s40, s40, 0x1100000
	s_addc_u32 s41, s41, 0
	global_load_lds_dwordx4 v170, s[40:41]
	s_add_i32 m0, s5, 24576
	s_add_u32 s40, s40, 0x80
	s_addc_u32 s41, s41, 0
	global_load_lds_dwordx4 v170, s[40:41]
.Lattn_pfkb_f:
	v_add_f32_e32 v191, v173, v233
	v_add_f32_e32 v254, v179, v234
	v_add_f32_e32 v255, v180, v235
	s_cmp_lg_u32 s35, 0
	s_cbranch_scc0 .Lattn_pfvt_f
	s_add_i32 s2, s31, 0
	s_and_b32 s2, s2, 31
	s_lshl_b32 s2, s2, 7
	s_add_i32 m0, s5, 65536
	s_add_u32 s44, s10, s2
	s_addc_u32 s45, s11, 0
	s_add_u32 s44, s44, 0x2000
	s_addc_u32 s45, s45, 0
	global_load_lds_dwordx4 v172, s[44:45]
	s_add_i32 m0, s5, 73728
	s_add_u32 s44, s44, 0x204000
	s_addc_u32 s45, s45, 0
	global_load_lds_dwordx4 v172, s[44:45]
.Lattn_pfvt_f:
	v_cvt_pk_bf16_f32 v144, v171, v173
	v_cvt_pk_bf16_f32 v145, v179, v180
	v_cvt_pk_bf16_f32 v146, v232, v233
	v_cvt_pk_bf16_f32 v147, v234, v235
	v_exp_f32_e32 v171, v72
	v_exp_f32_e32 v173, v73
	v_exp_f32_e32 v179, v74
	v_exp_f32_e32 v180, v75
	v_exp_f32_e32 v232, v76
	v_exp_f32_e32 v233, v77
	v_exp_f32_e32 v234, v78
	v_exp_f32_e32 v235, v79
	v_add_f32_e32 v190, v190, v171
	v_add_f32_e32 v191, v191, v173
	v_add_f32_e32 v254, v254, v179
	v_add_f32_e32 v255, v255, v180
	v_add_f32_e32 v190, v190, v232
	v_add_f32_e32 v191, v191, v233
	v_add_f32_e32 v254, v254, v234
	v_add_f32_e32 v255, v255, v235
	v_cvt_pk_bf16_f32 v148, v171, v173
	v_cvt_pk_bf16_f32 v149, v179, v180
	v_cvt_pk_bf16_f32 v150, v232, v233
	v_cvt_pk_bf16_f32 v151, v234, v235
	v_exp_f32_e32 v171, v80
	v_exp_f32_e32 v173, v81
	v_exp_f32_e32 v179, v82
	v_exp_f32_e32 v180, v83
	v_exp_f32_e32 v232, v84
	v_exp_f32_e32 v233, v85
	v_exp_f32_e32 v234, v86
	v_exp_f32_e32 v235, v87
	v_add_f32_e32 v190, v190, v171
	v_add_f32_e32 v191, v191, v173
	v_add_f32_e32 v254, v254, v179
	v_add_f32_e32 v255, v255, v180
	v_add_f32_e32 v190, v190, v232
	v_add_f32_e32 v191, v191, v233
	v_add_f32_e32 v254, v254, v234
	v_add_f32_e32 v255, v255, v235
	v_cvt_pk_bf16_f32 v152, v171, v173
	v_cvt_pk_bf16_f32 v153, v179, v180
	v_cvt_pk_bf16_f32 v154, v232, v233
	v_cvt_pk_bf16_f32 v155, v234, v235
	v_exp_f32_e32 v171, v88
	v_exp_f32_e32 v173, v89
	v_exp_f32_e32 v179, v90
	v_exp_f32_e32 v180, v91
	v_exp_f32_e32 v232, v92
	v_exp_f32_e32 v233, v93
	v_exp_f32_e32 v234, v94
	v_exp_f32_e32 v235, v95
	v_add_f32_e32 v190, v190, v171
	v_add_f32_e32 v191, v191, v173
	v_add_f32_e32 v254, v254, v179
	v_add_f32_e32 v255, v255, v180
	v_add_f32_e32 v190, v190, v232
	v_add_f32_e32 v191, v191, v233
	v_add_f32_e32 v254, v254, v234
	v_add_f32_e32 v255, v255, v235
	v_add_f32_e32 v190, v190, v254
	v_add_f32_e32 v191, v191, v255
	v_add_f32_e32 v190, v190, v191
	v_cmp_ngt_f32_e32 vcc, 0x71800000, v190
	v_cvt_pk_bf16_f32 v156, v171, v173
	v_cvt_pk_bf16_f32 v157, v179, v180
	v_cvt_pk_bf16_f32 v158, v232, v233
	v_cvt_pk_bf16_f32 v159, v234, v235
	s_nop 0
	s_cbranch_vccnz .Lattn_redo_T30
	v_add_f32_e32 v167, v167, v190
	s_cmp_lg_u32 s14, 0
	s_cbranch_scc1 .Lattn_tb15
	s_cmp_lg_u32 s35, 0
	s_cbranch_scc1 .Lattn_tb15_w6
	s_waitcnt vmcnt(0)
	s_branch .Lattn_tb15_wd

.Lattn_pfq_f:
	v_exp_f32_e32 v180, v99
	v_exp_f32_e32 v232, v100
	v_exp_f32_e32 v233, v101
	v_exp_f32_e32 v234, v102
	v_exp_f32_e32 v235, v103
	v_add_f32_e32 v190, v171, v232
	v_add_f32_e32 v191, v173, v233
	v_add_f32_e32 v254, v179, v234
	v_add_f32_e32 v255, v180, v235
	v_cvt_pk_bf16_f32 v144, v171, v173
	v_cvt_pk_bf16_f32 v145, v179, v180
	v_cvt_pk_bf16_f32 v146, v232, v233
	v_cvt_pk_bf16_f32 v147, v234, v235
	v_exp_f32_e32 v171, v104
	v_exp_f32_e32 v173, v105
	v_exp_f32_e32 v179, v106
	v_exp_f32_e32 v180, v107
	v_exp_f32_e32 v232, v108
	v_exp_f32_e32 v233, v109
	v_exp_f32_e32 v234, v110
	v_exp_f32_e32 v235, v111
	v_add_f32_e32 v190, v190, v171
	v_add_f32_e32 v191, v191, v173
	v_add_f32_e32 v254, v254, v179
	v_add_f32_e32 v255, v255, v180
	v_add_f32_e32 v190, v190, v232
	v_add_f32_e32 v191, v191, v233
	v_add_f32_e32 v254, v254, v234
	v_add_f32_e32 v255, v255, v235
	v_cvt_pk_bf16_f32 v148, v171, v173
	v_cvt_pk_bf16_f32 v149, v179, v180
	v_cvt_pk_bf16_f32 v150, v232, v233
	v_cvt_pk_bf16_f32 v151, v234, v235
	v_exp_f32_e32 v171, v112
	v_exp_f32_e32 v173, v113
	v_exp_f32_e32 v179, v114
	v_exp_f32_e32 v180, v115
	v_exp_f32_e32 v232, v116
	v_exp_f32_e32 v233, v117
	v_exp_f32_e32 v234, v118
	v_exp_f32_e32 v235, v119
	v_add_f32_e32 v190, v190, v171
	v_add_f32_e32 v191, v191, v173
	v_add_f32_e32 v254, v254, v179
	v_add_f32_e32 v255, v255, v180
	v_add_f32_e32 v190, v190, v232
	v_add_f32_e32 v191, v191, v233
	v_add_f32_e32 v254, v254, v234
	v_add_f32_e32 v255, v255, v235
	v_cvt_pk_bf16_f32 v152, v171, v173
	v_cvt_pk_bf16_f32 v153, v179, v180
	v_cvt_pk_bf16_f32 v154, v232, v233
	v_cvt_pk_bf16_f32 v155, v234, v235
	v_exp_f32_e32 v171, v120
	v_exp_f32_e32 v173, v121
	v_exp_f32_e32 v179, v122
	v_exp_f32_e32 v180, v123
	v_exp_f32_e32 v232, v124
	v_exp_f32_e32 v233, v125
	v_exp_f32_e32 v234, v126
	v_exp_f32_e32 v235, v127
	v_add_f32_e32 v190, v190, v171
	v_add_f32_e32 v191, v191, v173
	v_add_f32_e32 v254, v254, v179
	v_add_f32_e32 v255, v255, v180
	v_add_f32_e32 v190, v190, v232
	v_add_f32_e32 v191, v191, v233
	v_add_f32_e32 v254, v254, v234
	v_add_f32_e32 v255, v255, v235
	v_add_f32_e32 v190, v190, v254
	v_add_f32_e32 v191, v191, v255
	v_add_f32_e32 v190, v190, v191
	v_cmp_ngt_f32_e32 vcc, 0x71800000, v190
	v_cvt_pk_bf16_f32 v156, v171, v173
	v_cvt_pk_bf16_f32 v157, v179, v180
	v_cvt_pk_bf16_f32 v158, v232, v233
	v_cvt_pk_bf16_f32 v159, v234, v235
	s_nop 0
	s_cbranch_vccnz .Lattn_redo_T31
	v_add_f32_e32 v167, v167, v190
